# attention tile loop: K/V rows requested two tiles ahead into two alternating register sets (vmcnt(4) at the tile bottom), on top of v23
# speedup vs baseline: 1.0005x; 1.0005x over previous
; #define LAS __attribute__((address_space(3)))
; #define SB_LOAD(k0_) do { _Pragma("unroll") for (int i_ = 0; i_ < 2; ++i_) { const size_t o_ = gbase + (size_t)((k0_) + srow + 32 * i_) * SBW; rk[i_] = *(const v4u*)(Kb + o_); rv[i_] = *(const v4u*)(Vb + o_); } } while (0)
; #define SB_WRITE(buf_) do { _Pragma("unroll") for (int i_ = 0; i_ < 2; ++i_) { *(LAS v4u*)(KB0 + (buf_) * 16384 + kwo + i_ * 8192) = rk[i_]; *(LAS v4u*)(VB0 + (buf_) * 16384 + vwo + i_ * 8192) = rv[i_]; } } while (0)
; __device__ __forceinline__ void sb_attn_unit(Frame& F, int b, int h, int qb, int half) {
;     ...
;     const int q0w = 256 * qb + 32 * F.wave;
;     LAS unsigned char* KB0 = F.lds + RING_OFF; LAS unsigned char* VB0 = F.lds + RING_OFF + 32768;
;     bf16x8 qf[8];
;     { const bf16* qp = Qb + ((size_t)b * T + q0w + r32) * SBW + h * HD + 8 * hh;
; #pragma unroll
;       for (int s = 0; s < 8; ++s) qf[s] = *(const bf16x8*)(qp + 16 * s); }
;     const float k1 = SB_SCALE * LOG2E, k2 = kin(12)[h] * LOG2E;
;     f32x16 oacc[4];
; #pragma unroll
;     for (int d = 0; d < 4; ++d)
; #pragma unroll
;         for (int i = 0; i < 16; ++i) oacc[d][i] = 0.f;
;     float R = 1.f;
;     const int nt = 2 * qb + 2, ktop = (half == 0) ? 4 * qb + 3 : 2 * qb + 1;
;     const int srow = F.tid >> 4, sch = F.tid & 15;
;     const size_t gbase = ((size_t)b * T) * SBW + h * HD + sch * 8;
;     v4u rk[2], rv[2];
;     ...
;     const unsigned kwo = (unsigned)((sch >> 1) * 1024 + srow * 32 + (((sch & 1) ^ ((srow >> 3) & 1)) * 16));
;     const unsigned vwo = (unsigned)((((srow >> 3) * 4 + (sch >> 2)) * 512) + (srow & 7) * 64 + (sch & 3) * 16);
;     ...
;     SB_LOAD(64 * ktop); SB_WRITE(0);
;     __syncthreads();
;     const int tq = (lane & 15) >> 2, tp = lane & 3, tblk = (lane >> 4) & 1;
;     const unsigned kro = (unsigned)(r32 * 32 + ((hh ^ ((r32 >> 3) & 1)) * 16));
;     const unsigned vro = (unsigned)((4 * hh + tq) * 64 + tblk * 32 + tp * 8);
.LBB0_1431:
	s_or_b64 exec, exec, s[10:11]
	s_ashr_i32 s12, s2, 5
	s_sub_i32 s30, 15, s12
	s_lshl_b32 s35, s30, 8
	s_bfe_u32 s33, s2, 0x10003
	s_add_i32 s35, s35, s40
	s_bfe_u32 s29, s2, 0x10004
	s_and_b32 s31, s2, 7
	s_lshl_b32 s2, s33, 12
	s_ashr_i32 s10, s35, 31
	s_add_u32 s2, s35, s2
	s_addc_u32 s10, s10, 0
	v_mov_b32_e32 v5, s10
	v_or_b32_e32 v4, s2, v182
	v_lshlrev_b64 v[4:5], 11, v[4:5]
	v_lshl_add_u64 v[4:5], s[46:47], 0, v[4:5]
	s_lshl_b32 s44, s31, 8
	v_lshl_add_u64 v[4:5], v[4:5], 0, s[44:45]
	v_lshl_add_u64 v[4:5], v[4:5], 0, v[154:155]
	s_movk_i32 s2, 0x60
	global_load_dwordx4 v[142:145], v[4:5], off
	global_load_dwordx4 v[138:141], v[4:5], off offset:32
	global_load_dwordx4 v[134:137], v[4:5], off offset:64
	global_load_dwordx4 v[130:133], v[4:5], off offset:96
	global_load_dwordx4 v[126:129], v[4:5], off offset:128
	global_load_dwordx4 v[122:125], v[4:5], off offset:160
	global_load_dwordx4 v[118:121], v[4:5], off offset:192
	global_load_dwordx4 v[114:117], v[4:5], off offset:224
	s_lshl_b32 s13, s30, 1
	s_lshl_b32 s14, s30, 2
	s_load_dwordx2 s[10:11], s[0:1], s2 offset:0x0
	s_lshl_b32 s2, s31, 2
	s_or_b32 s14, s14, 3
	s_or_b32 s13, s13, 1
	s_cmp_eq_u32 s29, 0
	s_cselect_b32 s36, s14, s13
	v_lshl_or_b32 v2, s33, 22, v150
	s_lshl_b32 s13, s36, 6
	v_lshl_or_b32 v160, s31, 7, v2
	v_or_b32_e32 v2, s13, v157
	v_mov_b32_e32 v161, v1
	v_lshlrev_b64 v[4:5], 10, v[2:3]
	v_lshl_add_u64 v[4:5], v[4:5], 0, v[160:161]
	v_lshlrev_b64 v[4:5], 1, v[4:5]
	v_lshl_add_u64 v[6:7], s[48:49], 0, v[4:5]
	v_lshl_add_u64 v[4:5], s[50:51], 0, v[4:5]
	v_or_b32_e32 v2, 32, v2
	global_load_dwordx4 v[66:69], v[6:7], off
	global_load_dwordx4 v[70:73], v[4:5], off
	v_lshlrev_b64 v[4:5], 10, v[2:3]
	v_lshl_add_u64 v[4:5], v[4:5], 0, v[160:161]
	v_lshlrev_b64 v[4:5], 1, v[4:5]
	v_lshl_add_u64 v[6:7], s[48:49], 0, v[4:5]
	v_lshl_add_u64 v[4:5], s[50:51], 0, v[4:5]
	global_load_dwordx4 v[74:77], v[6:7], off
	global_load_dwordx4 v[78:81], v[4:5], off
	v_mov_b32_e32 v2, s2
	s_waitcnt lgkmcnt(0)
	global_load_dword v82, v2, s[10:11]
	s_sub_i32 s98, s13, 64
	v_add_u32_e32 v240, s98, v157
	v_add_u32_e32 v242, 32, v240
	v_ashrrev_i32_e32 v241, 31, v240
	v_ashrrev_i32_e32 v243, 31, v242
	v_lshlrev_b64 v[240:241], 10, v[240:241]
	v_lshlrev_b64 v[242:243], 10, v[242:243]
	v_lshl_add_u64 v[240:241], v[240:241], 0, v[160:161]
	v_lshl_add_u64 v[242:243], v[242:243], 0, v[160:161]
	v_lshlrev_b64 v[240:241], 1, v[240:241]
	v_lshlrev_b64 v[242:243], 1, v[242:243]
	v_lshl_add_u64 v[244:245], s[48:49], 0, v[240:241]
	v_lshl_add_u64 v[246:247], s[50:51], 0, v[240:241]
	v_lshl_add_u64 v[248:249], s[48:49], 0, v[242:243]
	v_lshl_add_u64 v[240:241], s[50:51], 0, v[242:243]
	global_load_dwordx4 v[222:225], v[244:245], off
	global_load_dwordx4 v[226:229], v[246:247], off
	global_load_dwordx4 v[230:233], v[248:249], off
	global_load_dwordx4 v[234:237], v[240:241], off
	v_mov_b32_e32 v16, v3
	v_mov_b32_e32 v17, v3
	v_mov_b32_e32 v4, v3
	v_mov_b32_e32 v5, v3
	v_mov_b32_e32 v6, v3
	v_mov_b32_e32 v7, v3
	v_mov_b32_e32 v8, v3
	v_mov_b32_e32 v9, v3
	v_mov_b32_e32 v10, v3
	v_mov_b32_e32 v11, v3
	v_mov_b32_e32 v12, v3
	v_mov_b32_e32 v13, v3
	v_mov_b32_e32 v14, v3
	v_mov_b32_e32 v15, v3
	v_or_b32_e32 v156, s35, v182
	s_lshl_b32 s2, s12, 1
	v_mov_b32_e32 v2, v3
	v_mov_b64_e32 v[32:33], v[16:17]
	v_mov_b64_e32 v[48:49], v[16:17]
	v_mov_b64_e32 v[64:65], v[16:17]
	s_mov_b32 s37, 0
	v_mov_b32_e32 v159, 1.0
	v_mov_b32_e32 v151, v156
	s_or_b32 s44, s35, 31
	s_sub_i32 s41, 31, s2
	s_or_b32 s52, s13, 63
	v_mov_b64_e32 v[30:31], v[14:15]
	v_mov_b64_e32 v[28:29], v[12:13]
	v_mov_b64_e32 v[26:27], v[10:11]
	v_mov_b64_e32 v[24:25], v[8:9]
	v_mov_b64_e32 v[22:23], v[6:7]
	v_mov_b64_e32 v[20:21], v[4:5]
	v_mov_b64_e32 v[18:19], v[2:3]
	v_mov_b64_e32 v[46:47], v[14:15]
	v_mov_b64_e32 v[44:45], v[12:13]
	v_mov_b64_e32 v[42:43], v[10:11]
	v_mov_b64_e32 v[40:41], v[8:9]
	v_mov_b64_e32 v[38:39], v[6:7]
	v_mov_b64_e32 v[36:37], v[4:5]
	v_mov_b64_e32 v[34:35], v[2:3]
	v_mov_b64_e32 v[62:63], v[14:15]
	v_mov_b64_e32 v[60:61], v[12:13]
	v_mov_b64_e32 v[58:59], v[10:11]
	v_mov_b64_e32 v[56:57], v[8:9]
	v_mov_b64_e32 v[54:55], v[6:7]
	v_mov_b64_e32 v[52:53], v[4:5]
	v_mov_b64_e32 v[50:51], v[2:3]
	s_waitcnt vmcnt(8)
	ds_write_b128 v162, v[66:69]
	s_waitcnt vmcnt(7)
	ds_write_b128 v163, v[70:73] offset:32768
	s_waitcnt vmcnt(6)
	ds_write_b128 v162, v[74:77] offset:8192
	s_waitcnt vmcnt(5)
	ds_write_b128 v163, v[78:81] offset:40960
	v_mov_b64_e32 v[80:81], v[16:17]
	s_waitcnt vmcnt(4)
	v_mul_f32_e32 v170, 0x3fb8aa3b, v82
	v_mov_b64_e32 v[78:79], v[14:15]
	v_mov_b64_e32 v[76:77], v[12:13]
	v_mov_b64_e32 v[74:75], v[10:11]
	v_mov_b64_e32 v[72:73], v[8:9]
	v_mov_b64_e32 v[70:71], v[6:7]
	v_mov_b64_e32 v[68:69], v[4:5]
	v_mov_b64_e32 v[66:67], v[2:3]
	s_waitcnt lgkmcnt(0)
	s_barrier
	s_branch .LBB0_1434

; #define SB_WRITE(buf_) do { _Pragma("unroll") for (int i_ = 0; i_ < 2; ++i_) { *(LAS v4u*)(KB0 + (buf_) * 16384 + kwo + i_ * 8192) = rk[i_]; *(LAS v4u*)(VB0 + (buf_) * 16384 + vwo + i_ * 8192) = rv[i_]; } } while (0)
; __device__ __forceinline__ void sb_attn_unit(Frame& F, int b, int h, int qb, int half) {
;     ...
;         if (it + 1 < nt) SB_WRITE(buf ^ 1);
;         __syncthreads();
.LBB0_1433:
	s_xor_b32 s2, s53, 0x4000
	v_add_u32_e32 v2, s2, v162
	v_add_u32_e32 v16, s2, v163
	s_cmp_eq_u32 s99, 0
	s_cbranch_scc1 .Lsb_w0
	s_waitcnt vmcnt(4)
	s_branch .Lsb_w1

; #define SB_LOAD(k0_) do { _Pragma("unroll") for (int i_ = 0; i_ < 2; ++i_) { const size_t o_ = gbase + (size_t)((k0_) + srow + 32 * i_) * SBW; rk[i_] = *(const v4u*)(Kb + o_); rv[i_] = *(const v4u*)(Vb + o_); } } while (0)
; #define SB_WRITE(buf_) do { _Pragma("unroll") for (int i_ = 0; i_ < 2; ++i_) { *(LAS v4u*)(KB0 + (buf_) * 16384 + kwo + i_ * 8192) = rk[i_]; *(LAS v4u*)(VB0 + (buf_) * 16384 + vwo + i_ * 8192) = rv[i_]; } } while (0)
; __device__ __forceinline__ void sb_attn_unit(Frame& F, int b, int h, int qb, int half) {
;     ...
;     const unsigned kwo = (unsigned)((sch >> 1) * 1024 + srow * 32 + (((sch & 1) ^ ((srow >> 3) & 1)) * 16));
;     const unsigned vwo = (unsigned)((((srow >> 3) * 4 + (sch >> 2)) * 512) + (srow & 7) * 64 + (sch & 3) * 16);
;     ...
;     SB_LOAD(64 * ktop); SB_WRITE(0);
;     __syncthreads();
;     const int tq = (lane & 15) >> 2, tp = lane & 3, tblk = (lane >> 4) & 1;
;     const unsigned kro = (unsigned)(r32 * 32 + ((hh ^ ((r32 >> 3) & 1)) * 16));
;     const unsigned vro = (unsigned)((4 * hh + tq) * 64 + tblk * 32 + tp * 8);
;     for (int it = 0; it < nt; ++it) {
;         const int kt = ktop - it, buf = it & 1, k0 = 64 * kt;
;         if (it + 1 < nt) SB_LOAD(64 * (kt - 1));
;     ...
;         if (it + 1 < nt) SB_WRITE(buf ^ 1);
;         __syncthreads();
.Lsb_w1:
	s_bitcmp1_b32 s37, 0
	s_cbranch_scc1 .Lsb_wrA
	ds_write_b128 v2, v[222:225]
	ds_write_b128 v16, v[226:229] offset:32768
	ds_write_b128 v2, v[230:233] offset:8192
	ds_write_b128 v16, v[234:237] offset:40960
	s_branch .Lsb_wrdone
.Lsb_wrA:
	ds_write_b128 v2, v[4:7]
	ds_write_b128 v16, v[8:11] offset:32768
	ds_write_b128 v2, v[12:15] offset:8192
	ds_write_b128 v16, v[146:149] offset:40960
.Lsb_wrdone:
	s_add_i32 s37, s37, 1
	s_sub_i32 s52, s52, 64
	s_cmp_eq_u32 s41, s37
	s_waitcnt lgkmcnt(0)
	s_barrier
	s_cbranch_scc1 .LBB0_1441
.LBB0_1434:
	v_add_u32_e32 v238, s52, v157
	v_add_u32_e32 v240, 0xffffff41, v238
	v_add_u32_e32 v242, 0xffffff61, v238
	v_ashrrev_i32_e32 v241, 31, v240
	v_ashrrev_i32_e32 v243, 31, v242
	v_lshlrev_b64 v[240:241], 10, v[240:241]
	v_lshlrev_b64 v[242:243], 10, v[242:243]
	v_lshl_add_u64 v[240:241], v[240:241], 0, v[160:161]
	v_lshl_add_u64 v[242:243], v[242:243], 0, v[160:161]
	v_lshlrev_b64 v[240:241], 1, v[240:241]
	v_lshlrev_b64 v[242:243], 1, v[242:243]
	v_lshl_add_u64 v[244:245], s[48:49], 0, v[240:241]
	v_lshl_add_u64 v[246:247], s[50:51], 0, v[240:241]
	v_lshl_add_u64 v[248:249], s[48:49], 0, v[242:243]
	v_lshl_add_u64 v[240:241], s[50:51], 0, v[242:243]
	s_add_i32 s98, s37, 1
	s_mov_b32 s99, 0
	s_cmp_eq_u32 s98, s41
	s_cbranch_scc1 .Lsb_noload
	s_mov_b32 s99, 4
	s_bitcmp1_b32 s37, 0
	s_cbranch_scc1 .Lsb_loadB
	global_load_dwordx4 v[4:7], v[244:245], off
	global_load_dwordx4 v[8:11], v[246:247], off
	global_load_dwordx4 v[12:15], v[248:249], off
	global_load_dwordx4 v[146:149], v[240:241], off
	s_branch .Lsb_noload
.Lsb_loadB:
	global_load_dwordx4 v[222:225], v[244:245], off
	global_load_dwordx4 v[226:229], v[246:247], off
	global_load_dwordx4 v[230:233], v[248:249], off
	global_load_dwordx4 v[234:237], v[240:241], off
.Lsb_noload:
	s_and_b32 s2, s37, 1
	s_sub_i32 s10, s52, 63
	s_cmp_lt_i32 s10, s44
	s_mov_b64 s[10:11], -1
	s_cbranch_scc1 .LBB0_1436
	s_lshl_b32 s53, s2, 14
	s_mov_b64 s[10:11], 0
